# P0 adaLN GEMV: weight rows prefetched 3 iterations ahead with scalar-base global loads and counted vmcnt waits
# speedup vs baseline: 1.0014x; 1.0014x over previous
; __device__ __forceinline__ void p0_prologue(const Args& A, char* lds, int vcu, int G) {
;     ...
;         const int col = cb * 512 + tid; float acc[8];
; #pragma unroll
;         for (int b = 0; b < 8; ++b) acc[b] = 0.f;
;         const float* wp = A.in[I_ADAW] + ((size_t)l * 1024 + kc * 128) * 3072 + col;
; #pragma unroll 16
;         for (int k = 0; k < 128; ++k) { const float w = __builtin_nontemporal_load(&wp[(size_t)k * 3072]);
.LBB0_292:
	s_or_b64 exec, exec, s[22:23]
	s_mul_i32 s56, s56, 6
	s_sub_i32 s21, s21, s56
	s_sext_i32_i8 s21, s21
	v_lshl_add_u32 v0, s21, 9, v16
	s_ashr_i32 s21, s20, 31
	s_lshl_b64 s[22:23], s[20:21], 10
	s_ashr_i32 s21, s55, 31
	s_add_u32 s22, s22, s55
	s_addc_u32 s21, s23, s21
	s_mulk_i32 s21, 0x3000
	s_mul_hi_u32 s23, s22, 0x3000
	s_add_i32 s23, s23, s21
	s_mulk_i32 s22, 0x3000
	s_add_u32 s22, s33, s22
	s_addc_u32 s23, s3, s23
	v_ashrrev_i32_e32 v1, 31, v0
	v_mov_b32_e32 v4, 0
	v_lshl_add_u64 v[2:3], v[0:1], 2, s[22:23]
	s_mov_b64 s[22:23], 0
	s_mov_b32 s21, 0
	v_mov_b32_e32 v5, v4
	v_mov_b32_e32 v10, v4
	v_mov_b32_e32 v11, v4
	v_mov_b32_e32 v8, v4
	v_mov_b32_e32 v9, v4
	v_mov_b32_e32 v6, v4
	v_mov_b32_e32 v7, v4
	v_and_b32_e32 v255, 63, v220
	v_lshlrev_b32_e32 v255, 2, v255
	v_readfirstlane_b32 s98, v2
	v_readfirstlane_b32 s99, v3
	s_nop 4
	global_load_dword v180, v255, s[98:99] nt
	s_add_u32 s100, s98, 0x3000
	s_addc_u32 s101, s99, 0
	global_load_dword v181, v255, s[100:101] nt
	s_add_u32 s100, s98, 0x6000
	s_addc_u32 s101, s99, 0
	global_load_dword v182, v255, s[100:101] nt
	s_add_u32 s100, s98, 0x9000
	s_addc_u32 s101, s99, 0
	global_load_dword v183, v255, s[100:101] nt
	s_add_u32 s100, s98, 0xc000
	s_addc_u32 s101, s99, 0
	global_load_dword v184, v255, s[100:101] nt
	s_add_u32 s100, s98, 0xf000
	s_addc_u32 s101, s99, 0
	global_load_dword v185, v255, s[100:101] nt
	s_add_u32 s100, s98, 0x12000
	s_addc_u32 s101, s99, 0
	global_load_dword v186, v255, s[100:101] nt
	s_add_u32 s100, s98, 0x15000
	s_addc_u32 s101, s99, 0
	global_load_dword v187, v255, s[100:101] nt
	s_add_u32 s100, s98, 0x18000
	s_addc_u32 s101, s99, 0
	global_load_dword v188, v255, s[100:101] nt
	s_add_u32 s100, s98, 0x1b000
	s_addc_u32 s101, s99, 0
	global_load_dword v189, v255, s[100:101] nt
	s_add_u32 s100, s98, 0x1e000
	s_addc_u32 s101, s99, 0
	global_load_dword v190, v255, s[100:101] nt
	s_add_u32 s100, s98, 0x21000
	s_addc_u32 s101, s99, 0
	global_load_dword v191, v255, s[100:101] nt
	s_add_u32 s100, s98, 0x24000
	s_addc_u32 s101, s99, 0
	global_load_dword v192, v255, s[100:101] nt
	s_add_u32 s100, s98, 0x27000
	s_addc_u32 s101, s99, 0
	global_load_dword v193, v255, s[100:101] nt
	s_add_u32 s100, s98, 0x2a000
	s_addc_u32 s101, s99, 0
	global_load_dword v194, v255, s[100:101] nt
	s_add_u32 s100, s98, 0x2d000
	s_addc_u32 s101, s99, 0
	global_load_dword v195, v255, s[100:101] nt
	s_add_u32 s100, s98, 0x30000
	s_addc_u32 s101, s99, 0
	global_load_dword v196, v255, s[100:101] nt
	s_add_u32 s100, s98, 0x33000
	s_addc_u32 s101, s99, 0
	global_load_dword v197, v255, s[100:101] nt
	s_add_u32 s100, s98, 0x36000
	s_addc_u32 s101, s99, 0
	global_load_dword v198, v255, s[100:101] nt
	s_add_u32 s100, s98, 0x39000
	s_addc_u32 s101, s99, 0
	global_load_dword v199, v255, s[100:101] nt
	s_add_u32 s100, s98, 0x3c000
	s_addc_u32 s101, s99, 0
	global_load_dword v200, v255, s[100:101] nt
	s_add_u32 s100, s98, 0x3f000
	s_addc_u32 s101, s99, 0
	global_load_dword v201, v255, s[100:101] nt
	s_add_u32 s100, s98, 0x42000
	s_addc_u32 s101, s99, 0
	global_load_dword v202, v255, s[100:101] nt
	s_add_u32 s100, s98, 0x45000
	s_addc_u32 s101, s99, 0
	global_load_dword v203, v255, s[100:101] nt
	s_add_u32 s100, s98, 0x48000
	s_addc_u32 s101, s99, 0
	global_load_dword v204, v255, s[100:101] nt
	s_add_u32 s100, s98, 0x4b000
	s_addc_u32 s101, s99, 0
	global_load_dword v205, v255, s[100:101] nt
	s_add_u32 s100, s98, 0x4e000
	s_addc_u32 s101, s99, 0
	global_load_dword v206, v255, s[100:101] nt
	s_add_u32 s100, s98, 0x51000
	s_addc_u32 s101, s99, 0
	global_load_dword v207, v255, s[100:101] nt
	s_add_u32 s100, s98, 0x54000
	s_addc_u32 s101, s99, 0
	global_load_dword v208, v255, s[100:101] nt
	s_add_u32 s100, s98, 0x57000
	s_addc_u32 s101, s99, 0
	global_load_dword v209, v255, s[100:101] nt
	s_add_u32 s100, s98, 0x5a000
	s_addc_u32 s101, s99, 0
	global_load_dword v210, v255, s[100:101] nt
	s_add_u32 s100, s98, 0x5d000
	s_addc_u32 s101, s99, 0
	global_load_dword v211, v255, s[100:101] nt
	s_add_u32 s100, s98, 0x60000
	s_addc_u32 s101, s99, 0
	global_load_dword v212, v255, s[100:101] nt
	s_add_u32 s100, s98, 0x63000
	s_addc_u32 s101, s99, 0
	global_load_dword v213, v255, s[100:101] nt
	s_add_u32 s100, s98, 0x66000
	s_addc_u32 s101, s99, 0
	global_load_dword v214, v255, s[100:101] nt
	s_add_u32 s100, s98, 0x69000
	s_addc_u32 s101, s99, 0
	global_load_dword v215, v255, s[100:101] nt
	s_add_u32 s100, s98, 0x6c000
	s_addc_u32 s101, s99, 0
	global_load_dword v216, v255, s[100:101] nt
	s_add_u32 s100, s98, 0x6f000
	s_addc_u32 s101, s99, 0
	global_load_dword v217, v255, s[100:101] nt
	s_add_u32 s100, s98, 0x72000
	s_addc_u32 s101, s99, 0
	global_load_dword v218, v255, s[100:101] nt
	s_add_u32 s100, s98, 0x75000
	s_addc_u32 s101, s99, 0
	global_load_dword v219, v255, s[100:101] nt
	s_add_u32 s100, s98, 0x78000
	s_addc_u32 s101, s99, 0
	global_load_dword v222, v255, s[100:101] nt
	s_add_u32 s100, s98, 0x7b000
	s_addc_u32 s101, s99, 0
	global_load_dword v223, v255, s[100:101] nt
	s_add_u32 s100, s98, 0x7e000
	s_addc_u32 s101, s99, 0
	global_load_dword v224, v255, s[100:101] nt
	s_add_u32 s100, s98, 0x81000
	s_addc_u32 s101, s99, 0
	global_load_dword v225, v255, s[100:101] nt
	s_add_u32 s100, s98, 0x84000
	s_addc_u32 s101, s99, 0
	global_load_dword v226, v255, s[100:101] nt
	s_add_u32 s100, s98, 0x87000
	s_addc_u32 s101, s99, 0
	global_load_dword v227, v255, s[100:101] nt
	s_add_u32 s100, s98, 0x8a000
	s_addc_u32 s101, s99, 0
	global_load_dword v228, v255, s[100:101] nt
	s_add_u32 s100, s98, 0x8d000
	s_addc_u32 s101, s99, 0
	global_load_dword v229, v255, s[100:101] nt
	s_waitcnt lgkmcnt(0)
	s_barrier
; __device__ __forceinline__ void p0_prologue(const Args& A, char* lds, int vcu, int G) {
;     ...
;         for (int k = 0; k < 128; ++k) { const float w = __builtin_nontemporal_load(&wp[(size_t)k * 3072]);
; #pragma unroll
;             for (int b = 0; b < 8; ++b) acc[b] += sc[b * 128 + k] * w; }
.LBB0_293:
	v_mov_b32_e32 v20, s21
	ds_read_b128 v[22:25], v20
	ds_read_b128 v[26:29], v20 offset:16
	ds_read_b128 v[30:33], v20 offset:512
	ds_read_b128 v[34:37], v20 offset:528
	ds_read_b128 v[38:41], v20 offset:1024
	ds_read_b128 v[42:45], v20 offset:1040
	ds_read_b128 v[46:49], v20 offset:1536
	ds_read_b128 v[50:53], v20 offset:1552
	ds_read_b128 v[54:57], v20 offset:2048
	ds_read_b128 v[58:61], v20 offset:2064
	ds_read_b128 v[62:65], v20 offset:2560
	ds_read_b128 v[66:69], v20 offset:2576
	ds_read_b128 v[70:73], v20 offset:3072
	ds_read_b128 v[74:77], v20 offset:3088
	ds_read_b128 v[78:81], v20 offset:3584
	ds_read_b128 v[82:85], v20 offset:3600
	ds_read_b128 v[86:89], v20 offset:32
	ds_read_b128 v[90:93], v20 offset:48
	ds_read_b128 v[94:97], v20 offset:544
	ds_read_b128 v[98:101], v20 offset:560
	ds_read_b128 v[102:105], v20 offset:1056
	ds_read_b128 v[106:109], v20 offset:1072
	ds_read_b128 v[110:113], v20 offset:1568
	ds_read_b128 v[114:117], v20 offset:1584
	ds_read_b128 v[118:121], v20 offset:2080
	ds_read_b128 v[122:125], v20 offset:2096
	ds_read_b128 v[126:129], v20 offset:2592
	ds_read_b128 v[130:133], v20 offset:2608
	ds_read_b128 v[134:137], v20 offset:3104
	ds_read_b128 v[138:141], v20 offset:3120
	ds_read_b128 v[142:145], v20 offset:3616
	ds_read_b128 v[146:149], v20 offset:3632
	s_waitcnt lgkmcnt(0)
	v_mov_b32_e32 v178, v22
	v_mov_b32_e32 v179, v30
	v_mov_b32_e32 v30, v23
	v_mov_b32_e32 v22, v24
	v_mov_b32_e32 v23, v32
	v_mov_b32_e32 v32, v25
	v_mov_b32_e32 v24, v38
	v_mov_b32_e32 v25, v46
	v_mov_b32_e32 v46, v39
	v_mov_b32_e32 v38, v40
	v_mov_b32_e32 v39, v48
	v_mov_b32_e32 v48, v41
	v_mov_b32_e32 v40, v54
	v_mov_b32_e32 v41, v62
	v_mov_b32_e32 v62, v55
	v_mov_b32_e32 v54, v56
	v_mov_b32_e32 v55, v64
	v_mov_b32_e32 v64, v57
	v_mov_b32_e32 v56, v70
	v_mov_b32_e32 v57, v78
	v_mov_b32_e32 v78, v71
	v_mov_b32_e32 v70, v72
	v_mov_b32_e32 v71, v80
	v_mov_b32_e32 v80, v73
	v_mov_b32_e32 v72, v26
	v_mov_b32_e32 v73, v34
	v_mov_b32_e32 v34, v27
	s_cmp_eq_u32 s22, 0x30000
	s_cbranch_scc1 .Lgv_it1
	s_cmp_eq_u32 s22, 0x60000
	s_cbranch_scc1 .Lgv_it2
	s_cmp_eq_u32 s22, 0x90000
	s_cbranch_scc1 .Lgv_it3
	s_cmp_eq_u32 s22, 0xc0000
	s_cbranch_scc1 .Lgv_it4
	s_cmp_eq_u32 s22, 0xf0000
	s_cbranch_scc1 .Lgv_it5
	s_cmp_eq_u32 s22, 0x120000
	s_cbranch_scc1 .Lgv_it6
	s_cmp_eq_u32 s22, 0x150000
	s_cbranch_scc1 .Lgv_it7
	s_waitcnt vmcnt(32)
	v_mov_b32_e32 v150, v180
	v_mov_b32_e32 v152, v181
	v_mov_b32_e32 v154, v182
	v_mov_b32_e32 v156, v183
	v_mov_b32_e32 v158, v184
	v_mov_b32_e32 v160, v185
	v_mov_b32_e32 v162, v186
	v_mov_b32_e32 v164, v187
	v_mov_b32_e32 v166, v188
	v_mov_b32_e32 v20, v189
	v_mov_b32_e32 v168, v190
	v_mov_b32_e32 v170, v191
	v_mov_b32_e32 v172, v192
	v_mov_b32_e32 v174, v193
	v_mov_b32_e32 v176, v194
	v_mov_b32_e32 v12, v195
	s_add_u32 s100, s98, 0x90000
	s_addc_u32 s101, s99, 0
	global_load_dword v180, v255, s[100:101] nt
	s_add_u32 s100, s98, 0x93000
	s_addc_u32 s101, s99, 0
	global_load_dword v181, v255, s[100:101] nt
	s_add_u32 s100, s98, 0x96000
	s_addc_u32 s101, s99, 0
	global_load_dword v182, v255, s[100:101] nt
	s_add_u32 s100, s98, 0x99000
	s_addc_u32 s101, s99, 0
	global_load_dword v183, v255, s[100:101] nt
	s_add_u32 s100, s98, 0x9c000
	s_addc_u32 s101, s99, 0
	global_load_dword v184, v255, s[100:101] nt
	s_add_u32 s100, s98, 0x9f000
	s_addc_u32 s101, s99, 0
	global_load_dword v185, v255, s[100:101] nt
	s_add_u32 s100, s98, 0xa2000
	s_addc_u32 s101, s99, 0
	global_load_dword v186, v255, s[100:101] nt
	s_add_u32 s100, s98, 0xa5000
	s_addc_u32 s101, s99, 0
	global_load_dword v187, v255, s[100:101] nt
	s_add_u32 s100, s98, 0xa8000
	s_addc_u32 s101, s99, 0
	global_load_dword v188, v255, s[100:101] nt
	s_add_u32 s100, s98, 0xab000
	s_addc_u32 s101, s99, 0
	global_load_dword v189, v255, s[100:101] nt
	s_add_u32 s100, s98, 0xae000
	s_addc_u32 s101, s99, 0
	global_load_dword v190, v255, s[100:101] nt
	s_add_u32 s100, s98, 0xb1000
	s_addc_u32 s101, s99, 0
	global_load_dword v191, v255, s[100:101] nt
	s_add_u32 s100, s98, 0xb4000
	s_addc_u32 s101, s99, 0
	global_load_dword v192, v255, s[100:101] nt
	s_add_u32 s100, s98, 0xb7000
	s_addc_u32 s101, s99, 0
	global_load_dword v193, v255, s[100:101] nt
	s_add_u32 s100, s98, 0xba000
	s_addc_u32 s101, s99, 0
	global_load_dword v194, v255, s[100:101] nt
	s_add_u32 s100, s98, 0xbd000
	s_addc_u32 s101, s99, 0
	global_load_dword v195, v255, s[100:101] nt
	s_branch .Lgv_join
.Lgv_it1:
	s_waitcnt vmcnt(32)
	v_mov_b32_e32 v150, v196
	v_mov_b32_e32 v152, v197
	v_mov_b32_e32 v154, v198
	v_mov_b32_e32 v156, v199
	v_mov_b32_e32 v158, v200
	v_mov_b32_e32 v160, v201
	v_mov_b32_e32 v162, v202
	v_mov_b32_e32 v164, v203
	v_mov_b32_e32 v166, v204
	v_mov_b32_e32 v20, v205
	v_mov_b32_e32 v168, v206
	v_mov_b32_e32 v170, v207
	v_mov_b32_e32 v172, v208
	v_mov_b32_e32 v174, v209
	v_mov_b32_e32 v176, v210
	v_mov_b32_e32 v12, v211
	s_add_u32 s100, s98, 0xc0000
	s_addc_u32 s101, s99, 0
	global_load_dword v196, v255, s[100:101] nt
	s_add_u32 s100, s98, 0xc3000
	s_addc_u32 s101, s99, 0
	global_load_dword v197, v255, s[100:101] nt
	s_add_u32 s100, s98, 0xc6000
	s_addc_u32 s101, s99, 0
	global_load_dword v198, v255, s[100:101] nt
	s_add_u32 s100, s98, 0xc9000
	s_addc_u32 s101, s99, 0
	global_load_dword v199, v255, s[100:101] nt
	s_add_u32 s100, s98, 0xcc000
	s_addc_u32 s101, s99, 0
	global_load_dword v200, v255, s[100:101] nt
	s_add_u32 s100, s98, 0xcf000
	s_addc_u32 s101, s99, 0
	global_load_dword v201, v255, s[100:101] nt
	s_add_u32 s100, s98, 0xd2000
	s_addc_u32 s101, s99, 0
	global_load_dword v202, v255, s[100:101] nt
	s_add_u32 s100, s98, 0xd5000
	s_addc_u32 s101, s99, 0
	global_load_dword v203, v255, s[100:101] nt
	s_add_u32 s100, s98, 0xd8000
	s_addc_u32 s101, s99, 0
	global_load_dword v204, v255, s[100:101] nt
	s_add_u32 s100, s98, 0xdb000
	s_addc_u32 s101, s99, 0
	global_load_dword v205, v255, s[100:101] nt
	s_add_u32 s100, s98, 0xde000
	s_addc_u32 s101, s99, 0
	global_load_dword v206, v255, s[100:101] nt
	s_add_u32 s100, s98, 0xe1000
	s_addc_u32 s101, s99, 0
	global_load_dword v207, v255, s[100:101] nt
	s_add_u32 s100, s98, 0xe4000
	s_addc_u32 s101, s99, 0
	global_load_dword v208, v255, s[100:101] nt
	s_add_u32 s100, s98, 0xe7000
	s_addc_u32 s101, s99, 0
	global_load_dword v209, v255, s[100:101] nt
	s_add_u32 s100, s98, 0xea000
	s_addc_u32 s101, s99, 0
	global_load_dword v210, v255, s[100:101] nt
	s_add_u32 s100, s98, 0xed000
	s_addc_u32 s101, s99, 0
	global_load_dword v211, v255, s[100:101] nt
	s_branch .Lgv_join
; __device__ __forceinline__ void p0_prologue(const Args& A, char* lds, int vcu, int G) {
;     ...
;         for (int k = 0; k < 128; ++k) { const float w = __builtin_nontemporal_load(&wp[(size_t)k * 3072]);
; #pragma unroll
;             for (int b = 0; b < 8; ++b) acc[b] += sc[b * 128 + k] * w; }
.Lgv_it2:
	s_waitcnt vmcnt(32)
	v_mov_b32_e32 v150, v212
	v_mov_b32_e32 v152, v213
	v_mov_b32_e32 v154, v214
	v_mov_b32_e32 v156, v215
	v_mov_b32_e32 v158, v216
	v_mov_b32_e32 v160, v217
	v_mov_b32_e32 v162, v218
	v_mov_b32_e32 v164, v219
	v_mov_b32_e32 v166, v222
	v_mov_b32_e32 v20, v223
	v_mov_b32_e32 v168, v224
	v_mov_b32_e32 v170, v225
	v_mov_b32_e32 v172, v226
	v_mov_b32_e32 v174, v227
	v_mov_b32_e32 v176, v228
	v_mov_b32_e32 v12, v229
	s_add_u32 s100, s98, 0xf0000
	s_addc_u32 s101, s99, 0
	global_load_dword v212, v255, s[100:101] nt
	s_add_u32 s100, s98, 0xf3000
	s_addc_u32 s101, s99, 0
	global_load_dword v213, v255, s[100:101] nt
	s_add_u32 s100, s98, 0xf6000
	s_addc_u32 s101, s99, 0
	global_load_dword v214, v255, s[100:101] nt
	s_add_u32 s100, s98, 0xf9000
	s_addc_u32 s101, s99, 0
	global_load_dword v215, v255, s[100:101] nt
	s_add_u32 s100, s98, 0xfc000
	s_addc_u32 s101, s99, 0
	global_load_dword v216, v255, s[100:101] nt
	s_add_u32 s100, s98, 0xff000
	s_addc_u32 s101, s99, 0
	global_load_dword v217, v255, s[100:101] nt
	s_add_u32 s100, s98, 0x102000
	s_addc_u32 s101, s99, 0
	global_load_dword v218, v255, s[100:101] nt
	s_add_u32 s100, s98, 0x105000
	s_addc_u32 s101, s99, 0
	global_load_dword v219, v255, s[100:101] nt
	s_add_u32 s100, s98, 0x108000
	s_addc_u32 s101, s99, 0
	global_load_dword v222, v255, s[100:101] nt
	s_add_u32 s100, s98, 0x10b000
	s_addc_u32 s101, s99, 0
	global_load_dword v223, v255, s[100:101] nt
	s_add_u32 s100, s98, 0x10e000
	s_addc_u32 s101, s99, 0
	global_load_dword v224, v255, s[100:101] nt
	s_add_u32 s100, s98, 0x111000
	s_addc_u32 s101, s99, 0
	global_load_dword v225, v255, s[100:101] nt
	s_add_u32 s100, s98, 0x114000
	s_addc_u32 s101, s99, 0
	global_load_dword v226, v255, s[100:101] nt
	s_add_u32 s100, s98, 0x117000
	s_addc_u32 s101, s99, 0
	global_load_dword v227, v255, s[100:101] nt
	s_add_u32 s100, s98, 0x11a000
	s_addc_u32 s101, s99, 0
	global_load_dword v228, v255, s[100:101] nt
	s_add_u32 s100, s98, 0x11d000
	s_addc_u32 s101, s99, 0
	global_load_dword v229, v255, s[100:101] nt
	s_branch .Lgv_join
.Lgv_it3:
	s_waitcnt vmcnt(32)
	v_mov_b32_e32 v150, v180
	v_mov_b32_e32 v152, v181
	v_mov_b32_e32 v154, v182
	v_mov_b32_e32 v156, v183
	v_mov_b32_e32 v158, v184
	v_mov_b32_e32 v160, v185
	v_mov_b32_e32 v162, v186
	v_mov_b32_e32 v164, v187
	v_mov_b32_e32 v166, v188
	v_mov_b32_e32 v20, v189
	v_mov_b32_e32 v168, v190
	v_mov_b32_e32 v170, v191
	v_mov_b32_e32 v172, v192
	v_mov_b32_e32 v174, v193
	v_mov_b32_e32 v176, v194
	v_mov_b32_e32 v12, v195
	s_add_u32 s100, s98, 0x120000
	s_addc_u32 s101, s99, 0
	global_load_dword v180, v255, s[100:101] nt
	s_add_u32 s100, s98, 0x123000
	s_addc_u32 s101, s99, 0
	global_load_dword v181, v255, s[100:101] nt
	s_add_u32 s100, s98, 0x126000
	s_addc_u32 s101, s99, 0
	global_load_dword v182, v255, s[100:101] nt
	s_add_u32 s100, s98, 0x129000
	s_addc_u32 s101, s99, 0
	global_load_dword v183, v255, s[100:101] nt
	s_add_u32 s100, s98, 0x12c000
	s_addc_u32 s101, s99, 0
	global_load_dword v184, v255, s[100:101] nt
	s_add_u32 s100, s98, 0x12f000
	s_addc_u32 s101, s99, 0
	global_load_dword v185, v255, s[100:101] nt
	s_add_u32 s100, s98, 0x132000
	s_addc_u32 s101, s99, 0
	global_load_dword v186, v255, s[100:101] nt
	s_add_u32 s100, s98, 0x135000
	s_addc_u32 s101, s99, 0
	global_load_dword v187, v255, s[100:101] nt
	s_add_u32 s100, s98, 0x138000
	s_addc_u32 s101, s99, 0
	global_load_dword v188, v255, s[100:101] nt
	s_add_u32 s100, s98, 0x13b000
	s_addc_u32 s101, s99, 0
	global_load_dword v189, v255, s[100:101] nt
	s_add_u32 s100, s98, 0x13e000
	s_addc_u32 s101, s99, 0
	global_load_dword v190, v255, s[100:101] nt
	s_add_u32 s100, s98, 0x141000
	s_addc_u32 s101, s99, 0
	global_load_dword v191, v255, s[100:101] nt
	s_add_u32 s100, s98, 0x144000
	s_addc_u32 s101, s99, 0
	global_load_dword v192, v255, s[100:101] nt
	s_add_u32 s100, s98, 0x147000
	s_addc_u32 s101, s99, 0
	global_load_dword v193, v255, s[100:101] nt
	s_add_u32 s100, s98, 0x14a000
	s_addc_u32 s101, s99, 0
	global_load_dword v194, v255, s[100:101] nt
	s_add_u32 s100, s98, 0x14d000
	s_addc_u32 s101, s99, 0
	global_load_dword v195, v255, s[100:101] nt
	s_branch .Lgv_join
.Lgv_it4:
	s_waitcnt vmcnt(32)
	v_mov_b32_e32 v150, v196
	v_mov_b32_e32 v152, v197
	v_mov_b32_e32 v154, v198
	v_mov_b32_e32 v156, v199
	v_mov_b32_e32 v158, v200
	v_mov_b32_e32 v160, v201
	v_mov_b32_e32 v162, v202
	v_mov_b32_e32 v164, v203
	v_mov_b32_e32 v166, v204
	v_mov_b32_e32 v20, v205
	v_mov_b32_e32 v168, v206
	v_mov_b32_e32 v170, v207
	v_mov_b32_e32 v172, v208
	v_mov_b32_e32 v174, v209
	v_mov_b32_e32 v176, v210
	v_mov_b32_e32 v12, v211
	s_add_u32 s100, s98, 0x150000
	s_addc_u32 s101, s99, 0
	global_load_dword v196, v255, s[100:101] nt
	s_add_u32 s100, s98, 0x153000
	s_addc_u32 s101, s99, 0
	global_load_dword v197, v255, s[100:101] nt
	s_add_u32 s100, s98, 0x156000
	s_addc_u32 s101, s99, 0
	global_load_dword v198, v255, s[100:101] nt
	s_add_u32 s100, s98, 0x159000
	s_addc_u32 s101, s99, 0
	global_load_dword v199, v255, s[100:101] nt
	s_add_u32 s100, s98, 0x15c000
	s_addc_u32 s101, s99, 0
	global_load_dword v200, v255, s[100:101] nt
	s_add_u32 s100, s98, 0x15f000
	s_addc_u32 s101, s99, 0
	global_load_dword v201, v255, s[100:101] nt
	s_add_u32 s100, s98, 0x162000
	s_addc_u32 s101, s99, 0
	global_load_dword v202, v255, s[100:101] nt
	s_add_u32 s100, s98, 0x165000
	s_addc_u32 s101, s99, 0
	global_load_dword v203, v255, s[100:101] nt
	s_add_u32 s100, s98, 0x168000
	s_addc_u32 s101, s99, 0
	global_load_dword v204, v255, s[100:101] nt
	s_add_u32 s100, s98, 0x16b000
	s_addc_u32 s101, s99, 0
	global_load_dword v205, v255, s[100:101] nt
	s_add_u32 s100, s98, 0x16e000
	s_addc_u32 s101, s99, 0
	global_load_dword v206, v255, s[100:101] nt
	s_add_u32 s100, s98, 0x171000
	s_addc_u32 s101, s99, 0
	global_load_dword v207, v255, s[100:101] nt
	s_add_u32 s100, s98, 0x174000
	s_addc_u32 s101, s99, 0
	global_load_dword v208, v255, s[100:101] nt
	s_add_u32 s100, s98, 0x177000
	s_addc_u32 s101, s99, 0
	global_load_dword v209, v255, s[100:101] nt
	s_add_u32 s100, s98, 0x17a000
	s_addc_u32 s101, s99, 0
	global_load_dword v210, v255, s[100:101] nt
	s_add_u32 s100, s98, 0x17d000
	s_addc_u32 s101, s99, 0
	global_load_dword v211, v255, s[100:101] nt
	s_branch .Lgv_join
; __device__ __forceinline__ void p0_prologue(const Args& A, char* lds, int vcu, int G) {
;     ...
;         for (int k = 0; k < 128; ++k) { const float w = __builtin_nontemporal_load(&wp[(size_t)k * 3072]);
; #pragma unroll
;             for (int b = 0; b < 8; ++b) acc[b] += sc[b * 128 + k] * w; }
.Lgv_it5:
	s_waitcnt vmcnt(32)
	v_mov_b32_e32 v150, v212
	v_mov_b32_e32 v152, v213
	v_mov_b32_e32 v154, v214
	v_mov_b32_e32 v156, v215
	v_mov_b32_e32 v158, v216
	v_mov_b32_e32 v160, v217
	v_mov_b32_e32 v162, v218
	v_mov_b32_e32 v164, v219
	v_mov_b32_e32 v166, v222
	v_mov_b32_e32 v20, v223
	v_mov_b32_e32 v168, v224
	v_mov_b32_e32 v170, v225
	v_mov_b32_e32 v172, v226
	v_mov_b32_e32 v174, v227
	v_mov_b32_e32 v176, v228
	v_mov_b32_e32 v12, v229
	s_branch .Lgv_join
.Lgv_it6:
	s_waitcnt vmcnt(16)
	v_mov_b32_e32 v150, v180
	v_mov_b32_e32 v152, v181
	v_mov_b32_e32 v154, v182
	v_mov_b32_e32 v156, v183
	v_mov_b32_e32 v158, v184
	v_mov_b32_e32 v160, v185
	v_mov_b32_e32 v162, v186
	v_mov_b32_e32 v164, v187
	v_mov_b32_e32 v166, v188
	v_mov_b32_e32 v20, v189
	v_mov_b32_e32 v168, v190
	v_mov_b32_e32 v170, v191
	v_mov_b32_e32 v172, v192
	v_mov_b32_e32 v174, v193
	v_mov_b32_e32 v176, v194
	v_mov_b32_e32 v12, v195
	s_branch .Lgv_join
.Lgv_it7:
	s_waitcnt vmcnt(0)
	v_mov_b32_e32 v150, v196
	v_mov_b32_e32 v152, v197
	v_mov_b32_e32 v154, v198
	v_mov_b32_e32 v156, v199
	v_mov_b32_e32 v158, v200
	v_mov_b32_e32 v160, v201
	v_mov_b32_e32 v162, v202
	v_mov_b32_e32 v164, v203
	v_mov_b32_e32 v166, v204
	v_mov_b32_e32 v20, v205
	v_mov_b32_e32 v168, v206
	v_mov_b32_e32 v170, v207
	v_mov_b32_e32 v172, v208
	v_mov_b32_e32 v174, v209
	v_mov_b32_e32 v176, v210
	v_mov_b32_e32 v12, v211
.Lgv_join:
	v_pk_fma_f32 v[10:11], v[150:151], v[178:179], v[10:11] op_sel_hi:[0,1,1]
	v_pk_fma_f32 v[8:9], v[150:151], v[24:25], v[8:9] op_sel_hi:[0,1,1]
	v_pk_fma_f32 v[6:7], v[150:151], v[40:41], v[6:7] op_sel_hi:[0,1,1]
	v_pk_fma_f32 v[4:5], v[150:151], v[56:57], v[4:5] op_sel_hi:[0,1,1]
	v_mov_b32_e32 v26, v28
	v_mov_b32_e32 v27, v36
	v_mov_b32_e32 v36, v29
	v_mov_b32_e32 v28, v42
	v_mov_b32_e32 v29, v50
	v_mov_b32_e32 v50, v43
	v_mov_b32_e32 v42, v44
	v_mov_b32_e32 v43, v52
	v_mov_b32_e32 v52, v45
	v_mov_b32_e32 v44, v58
	v_mov_b32_e32 v45, v66
	v_mov_b32_e32 v66, v59
	v_mov_b32_e32 v58, v60
	v_mov_b32_e32 v59, v68
	v_mov_b32_e32 v68, v61
	v_mov_b32_e32 v60, v74
	v_mov_b32_e32 v61, v82
	v_mov_b32_e32 v82, v75
	v_mov_b32_e32 v74, v76
	v_mov_b32_e32 v75, v84
	v_mov_b32_e32 v84, v77
	v_mov_b32_e32 v76, v86
	v_mov_b32_e32 v77, v94
	v_mov_b32_e32 v94, v87
	v_mov_b32_e32 v86, v88
	v_mov_b32_e32 v87, v96
	v_mov_b32_e32 v96, v89
	v_mov_b32_e32 v88, v102
	v_mov_b32_e32 v89, v110
	v_mov_b32_e32 v110, v103
	v_mov_b32_e32 v102, v104
	v_mov_b32_e32 v103, v112
	v_mov_b32_e32 v112, v105
	v_mov_b32_e32 v104, v118
	v_mov_b32_e32 v105, v126
	v_mov_b32_e32 v126, v119
	v_mov_b32_e32 v118, v120
	v_mov_b32_e32 v119, v128
	v_mov_b32_e32 v128, v121
	v_mov_b32_e32 v120, v134
	v_mov_b32_e32 v121, v142
	v_mov_b32_e32 v142, v135
	v_mov_b32_e32 v134, v136
	v_mov_b32_e32 v135, v144
	v_mov_b32_e32 v144, v137
	s_waitcnt lgkmcnt(0)
; __device__ __forceinline__ void p0_prologue(const Args& A, char* lds, int vcu, int G) {
;     ...
;         for (int k = 0; k < 128; ++k) { const float w = __builtin_nontemporal_load(&wp[(size_t)k * 3072]);
; #pragma unroll
;             for (int b = 0; b < 8; ++b) acc[b] += sc[b * 128 + k] * w; }
; #pragma unroll
;         for (int b = 0; b < 8; ++b) modp[((size_t)(kc * 2 + l) * 8 + b) * 3072 + col] = acc[b];
	v_pk_fma_f32 v[10:11], v[152:153], v[30:31], v[10:11] op_sel_hi:[0,1,1]
	v_pk_fma_f32 v[8:9], v[152:153], v[46:47], v[8:9] op_sel_hi:[0,1,1]
	v_pk_fma_f32 v[6:7], v[152:153], v[62:63], v[6:7] op_sel_hi:[0,1,1]
	v_pk_fma_f32 v[4:5], v[152:153], v[78:79], v[4:5] op_sel_hi:[0,1,1]
	v_pk_fma_f32 v[10:11], v[154:155], v[22:23], v[10:11] op_sel_hi:[0,1,1]
	v_pk_fma_f32 v[8:9], v[154:155], v[38:39], v[8:9] op_sel_hi:[0,1,1]
	v_pk_fma_f32 v[6:7], v[154:155], v[54:55], v[6:7] op_sel_hi:[0,1,1]
	v_pk_fma_f32 v[4:5], v[154:155], v[70:71], v[4:5] op_sel_hi:[0,1,1]
	v_pk_fma_f32 v[10:11], v[156:157], v[32:33], v[10:11] op_sel_hi:[0,1,1]
	v_pk_fma_f32 v[8:9], v[156:157], v[48:49], v[8:9] op_sel_hi:[0,1,1]
	v_pk_fma_f32 v[6:7], v[156:157], v[64:65], v[6:7] op_sel_hi:[0,1,1]
	v_pk_fma_f32 v[4:5], v[156:157], v[80:81], v[4:5] op_sel_hi:[0,1,1]
	v_pk_fma_f32 v[10:11], v[158:159], v[72:73], v[10:11] op_sel_hi:[0,1,1]
	v_pk_fma_f32 v[8:9], v[158:159], v[28:29], v[8:9] op_sel_hi:[0,1,1]
	v_pk_fma_f32 v[6:7], v[158:159], v[44:45], v[6:7] op_sel_hi:[0,1,1]
	v_pk_fma_f32 v[4:5], v[158:159], v[60:61], v[4:5] op_sel_hi:[0,1,1]
	v_pk_fma_f32 v[10:11], v[160:161], v[34:35], v[10:11] op_sel_hi:[0,1,1]
	v_pk_fma_f32 v[8:9], v[160:161], v[50:51], v[8:9] op_sel_hi:[0,1,1]
	v_pk_fma_f32 v[6:7], v[160:161], v[66:67], v[6:7] op_sel_hi:[0,1,1]
	v_pk_fma_f32 v[4:5], v[160:161], v[82:83], v[4:5] op_sel_hi:[0,1,1]
	v_pk_fma_f32 v[10:11], v[162:163], v[26:27], v[10:11] op_sel_hi:[0,1,1]
	v_pk_fma_f32 v[8:9], v[162:163], v[42:43], v[8:9] op_sel_hi:[0,1,1]
	v_pk_fma_f32 v[6:7], v[162:163], v[58:59], v[6:7] op_sel_hi:[0,1,1]
	v_pk_fma_f32 v[4:5], v[162:163], v[74:75], v[4:5] op_sel_hi:[0,1,1]
	v_pk_fma_f32 v[10:11], v[164:165], v[36:37], v[10:11] op_sel_hi:[0,1,1]
	v_pk_fma_f32 v[8:9], v[164:165], v[52:53], v[8:9] op_sel_hi:[0,1,1]
	v_pk_fma_f32 v[6:7], v[164:165], v[68:69], v[6:7] op_sel_hi:[0,1,1]
	v_pk_fma_f32 v[4:5], v[164:165], v[84:85], v[4:5] op_sel_hi:[0,1,1]
	v_pk_fma_f32 v[10:11], v[166:167], v[76:77], v[10:11] op_sel_hi:[0,1,1]
	v_pk_fma_f32 v[8:9], v[166:167], v[88:89], v[8:9] op_sel_hi:[0,1,1]
	v_pk_fma_f32 v[6:7], v[166:167], v[104:105], v[6:7] op_sel_hi:[0,1,1]
	v_pk_fma_f32 v[4:5], v[166:167], v[120:121], v[4:5] op_sel_hi:[0,1,1]
	v_pk_fma_f32 v[10:11], v[20:21], v[94:95], v[10:11] op_sel_hi:[0,1,1]
	v_pk_fma_f32 v[8:9], v[20:21], v[110:111], v[8:9] op_sel_hi:[0,1,1]
	v_pk_fma_f32 v[6:7], v[20:21], v[126:127], v[6:7] op_sel_hi:[0,1,1]
	v_pk_fma_f32 v[4:5], v[20:21], v[142:143], v[4:5] op_sel_hi:[0,1,1]
	v_pk_fma_f32 v[10:11], v[168:169], v[86:87], v[10:11] op_sel_hi:[0,1,1]
	v_pk_fma_f32 v[8:9], v[168:169], v[102:103], v[8:9] op_sel_hi:[0,1,1]
	v_pk_fma_f32 v[6:7], v[168:169], v[118:119], v[6:7] op_sel_hi:[0,1,1]
	v_pk_fma_f32 v[4:5], v[168:169], v[134:135], v[4:5] op_sel_hi:[0,1,1]
	v_mov_b32_e32 v136, v90
	v_mov_b32_e32 v137, v98
	v_mov_b32_e32 v98, v91
	v_mov_b32_e32 v90, v92
	v_mov_b32_e32 v91, v100
	v_mov_b32_e32 v100, v93
	v_mov_b32_e32 v92, v106
	v_mov_b32_e32 v93, v114
	v_mov_b32_e32 v114, v107
	v_mov_b32_e32 v106, v108
	v_mov_b32_e32 v107, v116
	v_mov_b32_e32 v116, v109
	v_mov_b32_e32 v108, v122
	v_mov_b32_e32 v109, v130
	v_mov_b32_e32 v130, v123
	v_mov_b32_e32 v122, v124
	v_mov_b32_e32 v123, v132
	v_mov_b32_e32 v132, v125
	v_mov_b32_e32 v124, v138
	v_mov_b32_e32 v125, v146
	v_pk_fma_f32 v[10:11], v[170:171], v[96:97], v[10:11] op_sel_hi:[0,1,1]
	v_pk_fma_f32 v[8:9], v[170:171], v[112:113], v[8:9] op_sel_hi:[0,1,1]
	v_pk_fma_f32 v[6:7], v[170:171], v[128:129], v[6:7] op_sel_hi:[0,1,1]
	v_pk_fma_f32 v[4:5], v[170:171], v[144:145], v[4:5] op_sel_hi:[0,1,1]
	v_mov_b32_e32 v146, v139
	v_pk_fma_f32 v[10:11], v[172:173], v[136:137], v[10:11] op_sel_hi:[0,1,1]
	v_pk_fma_f32 v[8:9], v[172:173], v[92:93], v[8:9] op_sel_hi:[0,1,1]
	v_pk_fma_f32 v[6:7], v[172:173], v[108:109], v[6:7] op_sel_hi:[0,1,1]
	v_pk_fma_f32 v[4:5], v[172:173], v[124:125], v[4:5] op_sel_hi:[0,1,1]
	s_add_u32 s22, s22, 0x30000
	v_mov_b32_e32 v138, v140
	v_mov_b32_e32 v139, v148
	v_pk_fma_f32 v[10:11], v[174:175], v[98:99], v[10:11] op_sel_hi:[0,1,1]
	v_pk_fma_f32 v[8:9], v[174:175], v[114:115], v[8:9] op_sel_hi:[0,1,1]
	v_pk_fma_f32 v[6:7], v[174:175], v[130:131], v[6:7] op_sel_hi:[0,1,1]
	v_pk_fma_f32 v[4:5], v[174:175], v[146:147], v[4:5] op_sel_hi:[0,1,1]
	s_addc_u32 s23, s23, 0
	s_add_i32 s21, s21, 64
	v_mov_b32_e32 v148, v141
	v_pk_fma_f32 v[10:11], v[176:177], v[90:91], v[10:11] op_sel_hi:[0,1,1]
	v_pk_fma_f32 v[8:9], v[176:177], v[106:107], v[8:9] op_sel_hi:[0,1,1]
	v_pk_fma_f32 v[6:7], v[176:177], v[122:123], v[6:7] op_sel_hi:[0,1,1]
	v_pk_fma_f32 v[4:5], v[176:177], v[138:139], v[4:5] op_sel_hi:[0,1,1]
	s_cmp_eq_u32 s22, 0x180000
	v_pk_fma_f32 v[10:11], v[12:13], v[100:101], v[10:11] op_sel_hi:[0,1,1]
	v_pk_fma_f32 v[8:9], v[12:13], v[116:117], v[8:9] op_sel_hi:[0,1,1]
	v_pk_fma_f32 v[6:7], v[12:13], v[132:133], v[6:7] op_sel_hi:[0,1,1]
	v_pk_fma_f32 v[4:5], v[12:13], v[148:149], v[4:5] op_sel_hi:[0,1,1]
	s_cbranch_scc0 .LBB0_293
	s_lshl_b32 s21, s54, 1
	s_add_i32 s21, s21, s20
	v_lshl_add_u64 v[0:1], v[0:1], 2, s[40:41]
	v_mad_i64_i32 v[0:1], s[20:21], s21, v19, v[0:1]
	v_add_co_u32_e32 v2, vcc, 0x3000, v0
	flat_store_dword v[0:1], v10
	s_nop 0
	v_addc_co_u32_e32 v3, vcc, 0, v1, vcc
	flat_store_dword v[2:3], v11
	v_add_co_u32_e32 v2, vcc, 0x6000, v0
	s_add_i32 s53, s53, s38
	s_nop 0
	v_addc_co_u32_e32 v3, vcc, 0, v1, vcc
	flat_store_dword v[2:3], v8
	v_add_co_u32_e32 v2, vcc, 0x9000, v0
	s_cmpk_gt_i32 s53, 0x5f
	s_nop 0
	v_addc_co_u32_e32 v3, vcc, 0, v1, vcc
	flat_store_dword v[2:3], v9
	v_add_co_u32_e32 v2, vcc, 0xc000, v0
	s_nop 1
	v_addc_co_u32_e32 v3, vcc, 0, v1, vcc
	flat_store_dword v[2:3], v6
	v_add_co_u32_e32 v2, vcc, 0xf000, v0
	s_nop 1
	v_addc_co_u32_e32 v3, vcc, 0, v1, vcc
	flat_store_dword v[2:3], v7
	v_add_co_u32_e32 v2, vcc, 0x12000, v0
	s_nop 1
	v_addc_co_u32_e32 v3, vcc, 0, v1, vcc
	v_add_co_u32_e32 v0, vcc, 0x15000, v0
	flat_store_dword v[2:3], v4
	s_nop 0
	v_addc_co_u32_e32 v1, vcc, 0, v1, vcc
	flat_store_dword v[0:1], v5
	s_cbranch_scc0 .LBB0_289
